# as v42 plus odd-mixer dwconv token loop unrolled x3 with a 3-slot row queue: row m+4 prefetched (was m+2), counted wait vmcnt(5), drained at exit
# baseline (speedup 1.0000x reference)
; __device__ __forceinline__ void unpack8(const u32x4 w, float (&f)[8]) { f[0] = bf_lo(w.x); f[1] = bf_hi(w.x); f[2] = bf_lo(w.y); f[3] = bf_hi(w.y); f[4] = bf_lo(w.z); f[5] = bf_hi(w.z); f[6] = bf_lo(w.w); f[7] = bf_hi(w.w); }
; __device__ __forceinline__ u32x4 pack8(const float (&f)[8]) { u32x4 w; w.x = cvt_pk_bf16(f[0], f[1]); w.y = cvt_pk_bf16(f[2], f[3]); w.z = cvt_pk_bf16(f[4], f[5]); w.w = cvt_pk_bf16(f[6], f[7]); return w; }
; __global__ void __launch_bounds__(NTHREADS) mk_fwd(Params P) {
;     ...
;                         const bf16_t* z0 = Z2 + (size_t)t0 * ZLD + lane * 8;
;                         u32x4 r0 = t0 >= 2 ? *(const u32x4*)(z0 - 2 * ZLD) : zero4, r1 = t0 >= 1 ? *(const u32x4*)(z0 - ZLD) : zero4, r2 = *(const u32x4*)z0;
;                         u32x4 r3 = (t0 + 1 < T) ? *(const u32x4*)(z0 + ZLD) : zero4;
;                         for (int m = t0; m < t1; ++m) {
;                             const int S = m < TP ? 8192 : 4096, pos = m & (S - 1);
;                             const u32x4 nx = (m + 2 < T) ? *(const u32x4*)(Z2 + (size_t)(m + 2) * ZLD + lane * 8) : zero4;
;                             float x0[8], x1[8], x2[8], x3[8], a8[8];
;                             unpack8(r0, x0); unpack8(r1, x1); unpack8(r2, x2); unpack8(r3, x3);
;                             const float f0 = pos >= 2 ? 1.f : 0.f, f1 = pos >= 1 ? 1.f : 0.f, f3 = pos < S - 1 ? 1.f : 0.f;
; #pragma unroll
;                             for (int j = 0; j < 8; ++j) a8[j] = bb[j] + w4[2][j] * x2[j] + f0 * w4[0][j] * x0[j] + f1 * w4[1][j] * x1[j] + f3 * w4[3][j] * x3[j];
;                             *(u32x4*)(XC + (size_t)m * 512 + lane * 8) = pack8(a8);
;                             r0 = r1; r1 = r2; r2 = r3; r3 = nx;
;                         }
.LBB0_940:
	s_ashr_i32 s3, s2, 31
	s_lshl_b64 s[0:1], s[2:3], 10
	s_waitcnt vmcnt(0)
	v_mov_b32_e32 v68, v25
	v_and_b32_e32 v25, 63, v56
	s_add_u32 s0, s4, s0
	v_mov_b32_e32 v57, v21
	v_mov_b32_e32 v21, v23
	v_mov_b32_e32 v23, v17
	v_mov_b32_e32 v17, v19
	v_lshl_add_u64 v[60:61], s[36:37], 0, v[80:81]
	v_lshlrev_b32_e32 v80, 4, v25
	s_addc_u32 s1, s5, s1
	v_swap_b32 v19, v38
	v_mov_b32_e32 v62, v31
	v_mov_b32_e32 v17, v36
	v_mov_b32_e32 v36, v23
	v_mov_b32_e32 v64, v29
	v_mov_b32_e32 v23, v34
	v_mov_b32_e32 v34, v21
	v_mov_b32_e32 v66, v27
	v_mov_b32_e32 v21, v32
	v_mov_b32_e32 v32, v57
	v_lshl_add_u64 v[70:71], s[0:1], 0, v[80:81]
	v_mov_b32_e32 v128, 0x1600
	s_add_i32 s0, s2, 2
	v_mad_i64_i32 v[126:127], s[0:1], s0, v128, v[60:61]
	global_load_dwordx4 v[118:121], v[126:127], off
	global_load_dword v129, v[126:127], off
	s_nop 4
	s_add_i32 s0, s2, 3
	v_mad_i64_i32 v[126:127], s[0:1], s0, v128, v[60:61]
	global_load_dwordx4 v[122:125], v[126:127], off
	global_load_dword v129, v[126:127], off
	s_nop 4
	s_branch .Loc0_hd
.Loc0_ld:
	s_add_i32 s0, s2, 4
	v_mov_b32_e32 v25, 0x1600
	v_mad_i64_i32 v[56:57], s[0:1], s0, v25, v[60:61]
	global_load_dwordx4 v[56:59], v[56:57], off
.Loc0_cmp:
	s_cmpk_lt_i32 s2, 0x4000
	s_movk_i32 s0, 0x1fff
	s_cselect_b32 s3, s0, 0xfff
	s_and_b32 s12, s3, s2
	s_cmp_gt_u32 s12, 1
	s_cselect_b64 s[0:1], -1, 0
	v_cndmask_b32_e64 v63, 0, 1.0, s[0:1]
	v_mul_f32_e32 v25, v63, v12
	v_lshlrev_b32_e32 v73, 16, v44
	v_lshlrev_b32_e32 v72, 16, v48
	v_pk_mul_f32 v[72:73], v[24:25], v[72:73]
	v_mul_f32_e32 v69, v63, v13
	v_add_f32_e32 v25, v4, v72
	v_add_f32_e32 v25, v25, v73
	v_and_b32_e32 v73, 0xffff0000, v44
	v_and_b32_e32 v72, 0xffff0000, v48
	v_pk_mul_f32 v[72:73], v[68:69], v[72:73]
	s_cmp_eq_u32 s12, s3
	v_add_f32_e32 v27, v5, v72
	v_add_f32_e32 v69, v27, v73
	v_mul_f32_e32 v27, v63, v14
	v_lshlrev_b32_e32 v73, 16, v45
	v_lshlrev_b32_e32 v72, 16, v49
	v_pk_mul_f32 v[72:73], v[26:27], v[72:73]
	s_cselect_b64 s[0:1], -1, 0
	s_cmp_eq_u32 s12, 0
	v_add_f32_e32 v27, v6, v72
	v_add_f32_e32 v27, v27, v73
	v_mul_f32_e32 v67, v63, v15
	v_and_b32_e32 v45, 0xffff0000, v45
	v_and_b32_e32 v44, 0xffff0000, v49
	v_cndmask_b32_e64 v73, 1.0, 0, s[0:1]
	s_cselect_b64 s[0:1], -1, 0
	v_pk_mul_f32 v[44:45], v[66:67], v[44:45]
	v_cndmask_b32_e64 v72, 1.0, 0, s[0:1]
	v_add_f32_e32 v29, v7, v44
	v_lshlrev_b32_e32 v75, 16, v52
	v_lshlrev_b32_e32 v74, 16, v40
	v_pk_mul_f32 v[76:77], v[72:73], v[20:21]
	v_add_f32_e32 v67, v29, v45
	v_mul_f32_e32 v29, v63, v8
	v_lshlrev_b32_e32 v45, 16, v46
	v_lshlrev_b32_e32 v44, 16, v50
	v_pk_mul_f32 v[74:75], v[76:77], v[74:75]
	v_pk_mul_f32 v[44:45], v[28:29], v[44:45]
	v_add_f32_e32 v25, v25, v74
	v_add_f32_e32 v29, v0, v44
	v_add_f32_e32 v25, v25, v75
	v_and_b32_e32 v75, 0xffff0000, v52
	v_and_b32_e32 v74, 0xffff0000, v40
	v_pk_mul_f32 v[76:77], v[72:73], v[32:33]
	v_add_f32_e32 v29, v29, v45
	v_mul_f32_e32 v65, v63, v9
	v_and_b32_e32 v45, 0xffff0000, v46
	v_and_b32_e32 v44, 0xffff0000, v50
	v_pk_mul_f32 v[74:75], v[76:77], v[74:75]
	v_pk_mul_f32 v[44:45], v[64:65], v[44:45]
	v_add_f32_e32 v65, v69, v74
	v_add_f32_e32 v65, v65, v75
	v_lshlrev_b32_e32 v75, 16, v53
	v_lshlrev_b32_e32 v74, 16, v41
	v_pk_mul_f32 v[76:77], v[72:73], v[22:23]
	v_add_f32_e32 v31, v1, v44
	v_pk_mul_f32 v[74:75], v[76:77], v[74:75]
	v_pk_mul_f32 v[76:77], v[72:73], v[34:35]
	v_add_f32_e32 v27, v27, v74
	v_add_f32_e32 v27, v27, v75
	v_and_b32_e32 v75, 0xffff0000, v53
	v_and_b32_e32 v74, 0xffff0000, v41
	v_pk_mul_f32 v[74:75], v[76:77], v[74:75]
	v_pk_mul_f32 v[76:77], v[72:73], v[16:17]
	v_add_f32_e32 v67, v67, v74
	v_add_f32_e32 v67, v67, v75
	v_lshlrev_b32_e32 v75, 16, v54
	v_lshlrev_b32_e32 v74, 16, v42
	v_pk_mul_f32 v[74:75], v[76:77], v[74:75]
	v_add_f32_e32 v46, v31, v45
	v_add_f32_e32 v29, v29, v74
	v_mul_f32_e32 v31, v63, v10
	v_lshlrev_b32_e32 v45, 16, v47
	v_lshlrev_b32_e32 v44, 16, v51
	v_add_f32_e32 v29, v29, v75
	v_and_b32_e32 v75, 0xffff0000, v54
	v_and_b32_e32 v74, 0xffff0000, v42
	v_pk_mul_f32 v[76:77], v[72:73], v[36:37]
	v_pk_mul_f32 v[44:45], v[30:31], v[44:45]
	v_pk_mul_f32 v[74:75], v[76:77], v[74:75]
	v_add_f32_e32 v31, v2, v44
	v_add_f32_e32 v46, v46, v74
	v_add_f32_e32 v31, v31, v45
	v_lshlrev_b32_e32 v45, 16, v55
	v_lshlrev_b32_e32 v44, 16, v43
	v_add_f32_e32 v69, v46, v75
	v_pk_mul_f32 v[74:75], v[72:73], v[18:19]
	v_mul_f32_e32 v63, v63, v11
	v_pk_mul_f32 v[44:45], v[74:75], v[44:45]
	s_add_i32 s2, s2, 1
	v_add_f32_e32 v31, v31, v44
	v_add_f32_e32 v31, v31, v45
	v_and_b32_e32 v45, 0xffff0000, v47
	v_and_b32_e32 v44, 0xffff0000, v51
	v_pk_mul_f32 v[44:45], v[62:63], v[44:45]
	v_pk_mul_f32 v[46:47], v[72:73], v[38:39]
	v_add_f32_e32 v44, v3, v44
	v_add_f32_e32 v63, v44, v45
	v_and_b32_e32 v45, 0xffff0000, v55
	v_and_b32_e32 v44, 0xffff0000, v43
	v_pk_mul_f32 v[44:45], v[46:47], v[44:45]
	s_mov_b64 s[0:1], 0x400
	v_add_f32_e32 v44, v63, v44
	v_add_f32_e32 v47, v44, v45
	v_cvt_pk_bf16_f32 v44, v25, v65
	v_cvt_pk_bf16_f32 v45, v27, v67
	v_cvt_pk_bf16_f32 v46, v29, v69
	v_cvt_pk_bf16_f32 v47, v31, v47
	global_store_dwordx4 v[70:71], v[44:47], off
	v_lshl_add_u64 v[70:71], v[70:71], 0, s[0:1]
	s_cmp_lt_i32 s2, s24
	v_mov_b64_e32 v[46:47], v[42:43]
	v_mov_b64_e32 v[44:45], v[40:41]
	v_mov_b64_e32 v[40:41], v[48:49]
	v_mov_b64_e32 v[42:43], v[50:51]
	v_mov_b64_e32 v[48:49], v[52:53]
	v_mov_b64_e32 v[50:51], v[54:55]
	s_waitcnt vmcnt(5)
	v_mov_b64_e32 v[52:53], v[118:119]
	v_mov_b64_e32 v[54:55], v[120:121]
	s_cbranch_scc0 .Loc_exit
	s_branch .Loc1_hd
.Loc1_ld:
	s_add_i32 s0, s2, 4
	v_mov_b32_e32 v25, 0x1600
	v_mad_i64_i32 v[118:119], s[0:1], s0, v25, v[60:61]
	global_load_dwordx4 v[118:121], v[118:119], off
; __device__ __forceinline__ void unpack8(const u32x4 w, float (&f)[8]) { f[0] = bf_lo(w.x); f[1] = bf_hi(w.x); f[2] = bf_lo(w.y); f[3] = bf_hi(w.y); f[4] = bf_lo(w.z); f[5] = bf_hi(w.z); f[6] = bf_lo(w.w); f[7] = bf_hi(w.w); }
; __device__ __forceinline__ u32x4 pack8(const float (&f)[8]) { u32x4 w; w.x = cvt_pk_bf16(f[0], f[1]); w.y = cvt_pk_bf16(f[2], f[3]); w.z = cvt_pk_bf16(f[4], f[5]); w.w = cvt_pk_bf16(f[6], f[7]); return w; }
; __global__ void __launch_bounds__(NTHREADS) mk_fwd(Params P) {
;     ...
;                         for (int m = t0; m < t1; ++m) {
;                             const int S = m < TP ? 8192 : 4096, pos = m & (S - 1);
;                             const u32x4 nx = (m + 2 < T) ? *(const u32x4*)(Z2 + (size_t)(m + 2) * ZLD + lane * 8) : zero4;
;                             float x0[8], x1[8], x2[8], x3[8], a8[8];
;                             unpack8(r0, x0); unpack8(r1, x1); unpack8(r2, x2); unpack8(r3, x3);
;                             const float f0 = pos >= 2 ? 1.f : 0.f, f1 = pos >= 1 ? 1.f : 0.f, f3 = pos < S - 1 ? 1.f : 0.f;
; #pragma unroll
;                             for (int j = 0; j < 8; ++j) a8[j] = bb[j] + w4[2][j] * x2[j] + f0 * w4[0][j] * x0[j] + f1 * w4[1][j] * x1[j] + f3 * w4[3][j] * x3[j];
;                             *(u32x4*)(XC + (size_t)m * 512 + lane * 8) = pack8(a8);
;                             r0 = r1; r1 = r2; r2 = r3; r3 = nx;
;                         }
.Loc1_cmp:
	s_cmpk_lt_i32 s2, 0x4000
	s_movk_i32 s0, 0x1fff
	s_cselect_b32 s3, s0, 0xfff
	s_and_b32 s12, s3, s2
	s_cmp_gt_u32 s12, 1
	s_cselect_b64 s[0:1], -1, 0
	v_cndmask_b32_e64 v63, 0, 1.0, s[0:1]
	v_mul_f32_e32 v25, v63, v12
	v_lshlrev_b32_e32 v73, 16, v44
	v_lshlrev_b32_e32 v72, 16, v48
	v_pk_mul_f32 v[72:73], v[24:25], v[72:73]
	v_mul_f32_e32 v69, v63, v13
	v_add_f32_e32 v25, v4, v72
	v_add_f32_e32 v25, v25, v73
	v_and_b32_e32 v73, 0xffff0000, v44
	v_and_b32_e32 v72, 0xffff0000, v48
	v_pk_mul_f32 v[72:73], v[68:69], v[72:73]
	s_cmp_eq_u32 s12, s3
	v_add_f32_e32 v27, v5, v72
	v_add_f32_e32 v69, v27, v73
	v_mul_f32_e32 v27, v63, v14
	v_lshlrev_b32_e32 v73, 16, v45
	v_lshlrev_b32_e32 v72, 16, v49
	v_pk_mul_f32 v[72:73], v[26:27], v[72:73]
	s_cselect_b64 s[0:1], -1, 0
	s_cmp_eq_u32 s12, 0
	v_add_f32_e32 v27, v6, v72
	v_add_f32_e32 v27, v27, v73
	v_mul_f32_e32 v67, v63, v15
	v_and_b32_e32 v45, 0xffff0000, v45
	v_and_b32_e32 v44, 0xffff0000, v49
	v_cndmask_b32_e64 v73, 1.0, 0, s[0:1]
	s_cselect_b64 s[0:1], -1, 0
	v_pk_mul_f32 v[44:45], v[66:67], v[44:45]
	v_cndmask_b32_e64 v72, 1.0, 0, s[0:1]
	v_add_f32_e32 v29, v7, v44
	v_lshlrev_b32_e32 v75, 16, v52
	v_lshlrev_b32_e32 v74, 16, v40
	v_pk_mul_f32 v[76:77], v[72:73], v[20:21]
	v_add_f32_e32 v67, v29, v45
	v_mul_f32_e32 v29, v63, v8
	v_lshlrev_b32_e32 v45, 16, v46
	v_lshlrev_b32_e32 v44, 16, v50
	v_pk_mul_f32 v[74:75], v[76:77], v[74:75]
	v_pk_mul_f32 v[44:45], v[28:29], v[44:45]
	v_add_f32_e32 v25, v25, v74
	v_add_f32_e32 v29, v0, v44
	v_add_f32_e32 v25, v25, v75
	v_and_b32_e32 v75, 0xffff0000, v52
	v_and_b32_e32 v74, 0xffff0000, v40
	v_pk_mul_f32 v[76:77], v[72:73], v[32:33]
	v_add_f32_e32 v29, v29, v45
	v_mul_f32_e32 v65, v63, v9
	v_and_b32_e32 v45, 0xffff0000, v46
	v_and_b32_e32 v44, 0xffff0000, v50
	v_pk_mul_f32 v[74:75], v[76:77], v[74:75]
	v_pk_mul_f32 v[44:45], v[64:65], v[44:45]
	v_add_f32_e32 v65, v69, v74
	v_add_f32_e32 v65, v65, v75
	v_lshlrev_b32_e32 v75, 16, v53
	v_lshlrev_b32_e32 v74, 16, v41
	v_pk_mul_f32 v[76:77], v[72:73], v[22:23]
	v_add_f32_e32 v31, v1, v44
	v_pk_mul_f32 v[74:75], v[76:77], v[74:75]
	v_pk_mul_f32 v[76:77], v[72:73], v[34:35]
	v_add_f32_e32 v27, v27, v74
	v_add_f32_e32 v27, v27, v75
	v_and_b32_e32 v75, 0xffff0000, v53
	v_and_b32_e32 v74, 0xffff0000, v41
	v_pk_mul_f32 v[74:75], v[76:77], v[74:75]
	v_pk_mul_f32 v[76:77], v[72:73], v[16:17]
	v_add_f32_e32 v67, v67, v74
	v_add_f32_e32 v67, v67, v75
	v_lshlrev_b32_e32 v75, 16, v54
	v_lshlrev_b32_e32 v74, 16, v42
	v_pk_mul_f32 v[74:75], v[76:77], v[74:75]
	v_add_f32_e32 v46, v31, v45
	v_add_f32_e32 v29, v29, v74
	v_mul_f32_e32 v31, v63, v10
	v_lshlrev_b32_e32 v45, 16, v47
	v_lshlrev_b32_e32 v44, 16, v51
	v_add_f32_e32 v29, v29, v75
	v_and_b32_e32 v75, 0xffff0000, v54
	v_and_b32_e32 v74, 0xffff0000, v42
	v_pk_mul_f32 v[76:77], v[72:73], v[36:37]
	v_pk_mul_f32 v[44:45], v[30:31], v[44:45]
	v_pk_mul_f32 v[74:75], v[76:77], v[74:75]
	v_add_f32_e32 v31, v2, v44
	v_add_f32_e32 v46, v46, v74
	v_add_f32_e32 v31, v31, v45
	v_lshlrev_b32_e32 v45, 16, v55
	v_lshlrev_b32_e32 v44, 16, v43
	v_add_f32_e32 v69, v46, v75
	v_pk_mul_f32 v[74:75], v[72:73], v[18:19]
	v_mul_f32_e32 v63, v63, v11
	v_pk_mul_f32 v[44:45], v[74:75], v[44:45]
	s_add_i32 s2, s2, 1
	v_add_f32_e32 v31, v31, v44
	v_add_f32_e32 v31, v31, v45
	v_and_b32_e32 v45, 0xffff0000, v47
	v_and_b32_e32 v44, 0xffff0000, v51
	v_pk_mul_f32 v[44:45], v[62:63], v[44:45]
	v_pk_mul_f32 v[46:47], v[72:73], v[38:39]
	v_add_f32_e32 v44, v3, v44
	v_add_f32_e32 v63, v44, v45
	v_and_b32_e32 v45, 0xffff0000, v55
	v_and_b32_e32 v44, 0xffff0000, v43
	v_pk_mul_f32 v[44:45], v[46:47], v[44:45]
	s_mov_b64 s[0:1], 0x400
	v_add_f32_e32 v44, v63, v44
	v_add_f32_e32 v47, v44, v45
	v_cvt_pk_bf16_f32 v44, v25, v65
	v_cvt_pk_bf16_f32 v45, v27, v67
	v_cvt_pk_bf16_f32 v46, v29, v69
	v_cvt_pk_bf16_f32 v47, v31, v47
	global_store_dwordx4 v[70:71], v[44:47], off
	v_lshl_add_u64 v[70:71], v[70:71], 0, s[0:1]
	s_cmp_lt_i32 s2, s24
	v_mov_b64_e32 v[46:47], v[42:43]
	v_mov_b64_e32 v[44:45], v[40:41]
	v_mov_b64_e32 v[40:41], v[48:49]
	v_mov_b64_e32 v[42:43], v[50:51]
	v_mov_b64_e32 v[48:49], v[52:53]
	v_mov_b64_e32 v[50:51], v[54:55]
	s_waitcnt vmcnt(5)
	v_mov_b64_e32 v[52:53], v[122:123]
	v_mov_b64_e32 v[54:55], v[124:125]
	s_cbranch_scc0 .Loc_exit
	s_branch .Loc2_hd
.Loc2_ld:
	s_add_i32 s0, s2, 4
	v_mov_b32_e32 v25, 0x1600
	v_mad_i64_i32 v[122:123], s[0:1], s0, v25, v[60:61]
	global_load_dwordx4 v[122:125], v[122:123], off
; __device__ __forceinline__ unsigned xb_ld(unsigned* p)              { return __hip_atomic_load(p, __ATOMIC_RELAXED, __HIP_MEMORY_SCOPE_AGENT); }
; __device__ __forceinline__ unsigned xb_add(unsigned* p, unsigned v) { return __hip_atomic_fetch_add(p, v, __ATOMIC_RELAXED, __HIP_MEMORY_SCOPE_AGENT); }
; #define XB_SPIN(cond, bar) do { unsigned _sp = 0; while (cond) {     \
;     if ((++_sp & 255u) == 0u) { if (xb_ld(&(bar)[XB_TMO])) break; if (_sp > XB_SPIN_CAP) { atomicAdd(&(bar)[XB_TMO], 1u); break; } } } } while (0)
; __device__ __forceinline__ void unpack8(const u32x4 w, float (&f)[8]) { f[0] = bf_lo(w.x); f[1] = bf_hi(w.x); f[2] = bf_lo(w.y); f[3] = bf_hi(w.y); f[4] = bf_lo(w.z); f[5] = bf_hi(w.z); f[6] = bf_lo(w.w); f[7] = bf_hi(w.w); }
; __device__ __forceinline__ void xcd_local_barrier(const XcdBarrier& b, unsigned nloc) {
;     asm volatile("s_waitcnt vmcnt(0)" ::: "memory");
;     __syncthreads();
;     if (threadIdx.x == 0) {
;         unsigned* bar = b.bar;
;         __builtin_amdgcn_s_waitcnt(0);
;         const unsigned lgen = b.st[5] + 1u; b.st[5] = lgen;
;         (void)xb_add(&bar[XL_CNT(b.x)], 1u);
;         const unsigned target = lgen * nloc;
;         XB_SPIN(xb_ld(&bar[XL_CNT(b.x)]) < target, bar);
; __global__ void __launch_bounds__(NTHREADS) mk_fwd(Params P) {
;     ...
;                         for (int m = t0; m < t1; ++m) {
;                             const int S = m < TP ? 8192 : 4096, pos = m & (S - 1);
;                             const u32x4 nx = (m + 2 < T) ? *(const u32x4*)(Z2 + (size_t)(m + 2) * ZLD + lane * 8) : zero4;
;                             float x0[8], x1[8], x2[8], x3[8], a8[8];
;                             unpack8(r0, x0); unpack8(r1, x1); unpack8(r2, x2); unpack8(r3, x3);
;                             const float f0 = pos >= 2 ? 1.f : 0.f, f1 = pos >= 1 ? 1.f : 0.f, f3 = pos < S - 1 ? 1.f : 0.f;
; #pragma unroll
;                             for (int j = 0; j < 8; ++j) a8[j] = bb[j] + w4[2][j] * x2[j] + f0 * w4[0][j] * x0[j] + f1 * w4[1][j] * x1[j] + f3 * w4[3][j] * x3[j];
;                             *(u32x4*)(XC + (size_t)m * 512 + lane * 8) = pack8(a8);
;                             r0 = r1; r1 = r2; r2 = r3; r3 = nx;
;                         }
.Loc2_cmp:
	s_cmpk_lt_i32 s2, 0x4000
	s_movk_i32 s0, 0x1fff
	s_cselect_b32 s3, s0, 0xfff
	s_and_b32 s12, s3, s2
	s_cmp_gt_u32 s12, 1
	s_cselect_b64 s[0:1], -1, 0
	v_cndmask_b32_e64 v63, 0, 1.0, s[0:1]
	v_mul_f32_e32 v25, v63, v12
	v_lshlrev_b32_e32 v73, 16, v44
	v_lshlrev_b32_e32 v72, 16, v48
	v_pk_mul_f32 v[72:73], v[24:25], v[72:73]
	v_mul_f32_e32 v69, v63, v13
	v_add_f32_e32 v25, v4, v72
	v_add_f32_e32 v25, v25, v73
	v_and_b32_e32 v73, 0xffff0000, v44
	v_and_b32_e32 v72, 0xffff0000, v48
	v_pk_mul_f32 v[72:73], v[68:69], v[72:73]
	s_cmp_eq_u32 s12, s3
	v_add_f32_e32 v27, v5, v72
	v_add_f32_e32 v69, v27, v73
	v_mul_f32_e32 v27, v63, v14
	v_lshlrev_b32_e32 v73, 16, v45
	v_lshlrev_b32_e32 v72, 16, v49
	v_pk_mul_f32 v[72:73], v[26:27], v[72:73]
	s_cselect_b64 s[0:1], -1, 0
	s_cmp_eq_u32 s12, 0
	v_add_f32_e32 v27, v6, v72
	v_add_f32_e32 v27, v27, v73
	v_mul_f32_e32 v67, v63, v15
	v_and_b32_e32 v45, 0xffff0000, v45
	v_and_b32_e32 v44, 0xffff0000, v49
	v_cndmask_b32_e64 v73, 1.0, 0, s[0:1]
	s_cselect_b64 s[0:1], -1, 0
	v_pk_mul_f32 v[44:45], v[66:67], v[44:45]
	v_cndmask_b32_e64 v72, 1.0, 0, s[0:1]
	v_add_f32_e32 v29, v7, v44
	v_lshlrev_b32_e32 v75, 16, v52
	v_lshlrev_b32_e32 v74, 16, v40
	v_pk_mul_f32 v[76:77], v[72:73], v[20:21]
	v_add_f32_e32 v67, v29, v45
	v_mul_f32_e32 v29, v63, v8
	v_lshlrev_b32_e32 v45, 16, v46
	v_lshlrev_b32_e32 v44, 16, v50
	v_pk_mul_f32 v[74:75], v[76:77], v[74:75]
	v_pk_mul_f32 v[44:45], v[28:29], v[44:45]
	v_add_f32_e32 v25, v25, v74
	v_add_f32_e32 v29, v0, v44
	v_add_f32_e32 v25, v25, v75
	v_and_b32_e32 v75, 0xffff0000, v52
	v_and_b32_e32 v74, 0xffff0000, v40
	v_pk_mul_f32 v[76:77], v[72:73], v[32:33]
	v_add_f32_e32 v29, v29, v45
	v_mul_f32_e32 v65, v63, v9
	v_and_b32_e32 v45, 0xffff0000, v46
	v_and_b32_e32 v44, 0xffff0000, v50
	v_pk_mul_f32 v[74:75], v[76:77], v[74:75]
	v_pk_mul_f32 v[44:45], v[64:65], v[44:45]
	v_add_f32_e32 v65, v69, v74
	v_add_f32_e32 v65, v65, v75
	v_lshlrev_b32_e32 v75, 16, v53
	v_lshlrev_b32_e32 v74, 16, v41
	v_pk_mul_f32 v[76:77], v[72:73], v[22:23]
	v_add_f32_e32 v31, v1, v44
	v_pk_mul_f32 v[74:75], v[76:77], v[74:75]
	v_pk_mul_f32 v[76:77], v[72:73], v[34:35]
	v_add_f32_e32 v27, v27, v74
	v_add_f32_e32 v27, v27, v75
	v_and_b32_e32 v75, 0xffff0000, v53
	v_and_b32_e32 v74, 0xffff0000, v41
	v_pk_mul_f32 v[74:75], v[76:77], v[74:75]
	v_pk_mul_f32 v[76:77], v[72:73], v[16:17]
	v_add_f32_e32 v67, v67, v74
	v_add_f32_e32 v67, v67, v75
	v_lshlrev_b32_e32 v75, 16, v54
	v_lshlrev_b32_e32 v74, 16, v42
	v_pk_mul_f32 v[74:75], v[76:77], v[74:75]
	v_add_f32_e32 v46, v31, v45
	v_add_f32_e32 v29, v29, v74
	v_mul_f32_e32 v31, v63, v10
	v_lshlrev_b32_e32 v45, 16, v47
	v_lshlrev_b32_e32 v44, 16, v51
	v_add_f32_e32 v29, v29, v75
	v_and_b32_e32 v75, 0xffff0000, v54
	v_and_b32_e32 v74, 0xffff0000, v42
	v_pk_mul_f32 v[76:77], v[72:73], v[36:37]
	v_pk_mul_f32 v[44:45], v[30:31], v[44:45]
	v_pk_mul_f32 v[74:75], v[76:77], v[74:75]
	v_add_f32_e32 v31, v2, v44
	v_add_f32_e32 v46, v46, v74
	v_add_f32_e32 v31, v31, v45
	v_lshlrev_b32_e32 v45, 16, v55
	v_lshlrev_b32_e32 v44, 16, v43
	v_add_f32_e32 v69, v46, v75
	v_pk_mul_f32 v[74:75], v[72:73], v[18:19]
	v_mul_f32_e32 v63, v63, v11
	v_pk_mul_f32 v[44:45], v[74:75], v[44:45]
	s_add_i32 s2, s2, 1
	v_add_f32_e32 v31, v31, v44
	v_add_f32_e32 v31, v31, v45
	v_and_b32_e32 v45, 0xffff0000, v47
	v_and_b32_e32 v44, 0xffff0000, v51
	v_pk_mul_f32 v[44:45], v[62:63], v[44:45]
	v_pk_mul_f32 v[46:47], v[72:73], v[38:39]
	v_add_f32_e32 v44, v3, v44
	v_add_f32_e32 v63, v44, v45
	v_and_b32_e32 v45, 0xffff0000, v55
	v_and_b32_e32 v44, 0xffff0000, v43
	v_pk_mul_f32 v[44:45], v[46:47], v[44:45]
	s_mov_b64 s[0:1], 0x400
	v_add_f32_e32 v44, v63, v44
	v_add_f32_e32 v47, v44, v45
	v_cvt_pk_bf16_f32 v44, v25, v65
	v_cvt_pk_bf16_f32 v45, v27, v67
	v_cvt_pk_bf16_f32 v46, v29, v69
	v_cvt_pk_bf16_f32 v47, v31, v47
	global_store_dwordx4 v[70:71], v[44:47], off
	v_lshl_add_u64 v[70:71], v[70:71], 0, s[0:1]
	s_cmp_lt_i32 s2, s24
	v_mov_b64_e32 v[46:47], v[42:43]
	v_mov_b64_e32 v[44:45], v[40:41]
	v_mov_b64_e32 v[40:41], v[48:49]
	v_mov_b64_e32 v[42:43], v[50:51]
	v_mov_b64_e32 v[48:49], v[52:53]
	v_mov_b64_e32 v[50:51], v[54:55]
	s_waitcnt vmcnt(5)
	v_mov_b64_e32 v[52:53], v[56:57]
	v_mov_b64_e32 v[54:55], v[58:59]
	s_cbranch_scc0 .Loc_exit
	s_branch .Loc0_hd
.Loc0_hd:
	s_cmpk_gt_i32 s2, 0x7ffb
	s_cbranch_scc0 .Loc0_ld
	s_waitcnt vmcnt(0)
	v_mov_b32_e32 v80, v81
	v_mov_b32_e32 v82, v81
	v_mov_b32_e32 v83, v81
	v_mov_b64_e32 v[56:57], v[80:81]
	v_mov_b64_e32 v[58:59], v[82:83]
	s_branch .Loc0_cmp
.Loc1_hd:
	s_cmpk_gt_i32 s2, 0x7ffb
	s_cbranch_scc0 .Loc1_ld
	s_waitcnt vmcnt(0)
	v_mov_b32_e32 v80, v81
	v_mov_b32_e32 v82, v81
	v_mov_b32_e32 v83, v81
	v_mov_b64_e32 v[118:119], v[80:81]
	v_mov_b64_e32 v[120:121], v[82:83]
	s_branch .Loc1_cmp
.Loc2_hd:
	s_cmpk_gt_i32 s2, 0x7ffb
	s_cbranch_scc0 .Loc2_ld
	s_waitcnt vmcnt(0)
	v_mov_b32_e32 v80, v81
	v_mov_b32_e32 v82, v81
	v_mov_b32_e32 v83, v81
	v_mov_b64_e32 v[122:123], v[80:81]
	v_mov_b64_e32 v[124:125], v[82:83]
	s_branch .Loc2_cmp
.Loc_exit:
	s_waitcnt vmcnt(0)
.LBB0_945:
	s_add_i32 s58, s33, 2
	s_cmp_ge_i32 s58, s89
	s_cbranch_scc1 .LBB0_1033
	s_cmp_lg_u32 s22, 0
	s_cbranch_scc0 .LBB0_960
	s_cmp_lt_u32 s23, 0x10000
	s_mov_b64 s[2:3], -1
	s_cbranch_scc1 .LBB0_967
	s_waitcnt vmcnt(0)
	s_waitcnt vmcnt(0)
	s_barrier
	s_mov_b64 s[2:3], exec
	v_readlane_b32 s0, v253, 2
	v_readlane_b32 s1, v253, 3
	s_and_b64 s[0:1], s[2:3], s[0:1]
	s_mov_b64 exec, s[0:1]
	s_cbranch_execz .LBB0_966
	v_readlane_b32 s0, v254, 55
	s_waitcnt vmcnt(0) expcnt(0) lgkmcnt(0)
	s_mov_b64 s[42:43], exec
	v_mov_b32_e32 v1, s0
	ds_read_b32 v0, v1
	s_waitcnt lgkmcnt(0)
	v_add_u32_e32 v0, 1, v0
	ds_write_b32 v1, v0
	v_mbcnt_lo_u32_b32 v1, s42, 0
	v_mbcnt_hi_u32_b32 v1, s43, v1
	v_cmp_eq_u32_e32 vcc, 0, v1
	s_and_saveexec_b64 s[44:45], vcc
	s_cbranch_execz .LBB0_951
	s_bcnt1_i32_b64 s0, s[42:43]
	v_mov_b32_e32 v1, s0
	v_readlane_b32 s0, v253, 10
	v_readlane_b32 s1, v253, 11
	s_nop 4
	global_atomic_add v81, v1, s[0:1]
